# hand-written weight transpose/convert tiles (all 32 row-pair loads in flight, scalar addressing, gains applied after the LDS transpose) replace the compiler's load-wait-per-pair loops
# speedup vs baseline: 1.0267x; 1.0119x over previous
; #define LAS __attribute__((address_space(3)))
; __device__ __forceinline__ void transpose_item(const float* W, const float* gk, int K, int N, bf16_t* WT, LAS float* scr, int item, int lane) {
;     const int nblk = N / 32, kb = item / nblk, nb = item % nblk, k0 = 64 * kb, n0 = 32 * nb;
; #pragma unroll 8
;     for (int i = 0; i < 32; ++i) { const int kk = 2 * i + (lane >> 5); float v = __builtin_nontemporal_load(W + (size_t)(k0 + kk) * N + n0 + (lane & 31));   if (gk) v *= gk[k0 + kk]; scr[kk * 33 + (lane & 31)] = v; }
; __device__ __forceinline__ void phase_prologue_rest(const Args& a, LAS unsigned char* lds, int G, const int bid, const int tid) {
;     ...
;     const int gw = (vb - ntab) * 8 + wave, NGW = (GB - ntab) * 8;
;     LAS float* scr = (LAS float*)(lds + wave * 16384);
;     constexpr int I_IN = 16 * 32, I_GLU = 8 * 16, I_OUT = 8 * 32, I_1 = 16 * 128, I_2 = 64 * 32, I_L = I_IN + I_GLU + I_OUT + I_1 + I_2;
;     for (int it = gw + I_IN; it < 2 * I_L; it += NGW) {
;         const int l = it / I_L; int r = it - l * I_L; unsigned char* wl = a.ws + WS_W + (size_t)l * WL_SZ;
;         if (r < I_IN) { transpose_item(a.in[7] + (size_t)l * DM * DM, a.in[5] + l * DM, DM, DM, (bf16_t*)(wl + WL_IN), scr, r, lane); continue; } r -= I_IN;
;         if (r < I_GLU) { transpose_item(a.in[16] + (size_t)l * WA * WA, nullptr, WA, WA, (bf16_t*)(wl + WL_GLU), scr, r, lane); continue; } r -= I_GLU;
;         if (r < I_OUT) { transpose_item(a.in[19] + (size_t)l * DM * DM, nullptr, DM, DM, (bf16_t*)(wl + WL_OUT), scr, r, lane); continue; } r -= I_OUT;
;         if (r < I_1) { transpose_item(a.in[20] + (size_t)l * DM * FF, a.in[6] + l * DM, DM, FF, (bf16_t*)(wl + WL_W1), scr, r, lane); continue; } r -= I_1;
;         transpose_item(a.in[21] + (size_t)l * FF * DM, nullptr, FF, DM, (bf16_t*)(wl + WL_W2), scr, r, lane);
;     }
.LBB0_798:
	v_writelane_b32 v255, s84, 13
	v_readlane_b32 s0, v253, 49
	s_cmp_ge_i32 s29, s0
	v_writelane_b32 v255, s85, 14
	s_cbranch_scc0 .LBB0_862
	v_readlane_b32 s0, v253, 49
	s_sub_i32 s0, s29, s0
	v_ashrrev_i32_e32 v0, 6, v162
	s_lshl_b32 s0, s0, 3
	v_add_u32_e32 v9, s0, v0
	v_add_u32_e32 v1, 0x200, v9
	s_movk_i32 s0, 0x2700
	v_cmp_gt_i32_e32 vcc, s0, v1
	s_and_saveexec_b64 s[4:5], vcc
	s_movk_i32 s24, 0x1ff
	s_cbranch_execz .LBB0_861
	v_lshlrev_b32_e32 v4, 3, v8
	v_lshlrev_b32_e32 v6, 14, v0
	v_lshrrev_b32_e32 v3, 3, v8
	v_and_b32_e32 v4, 56, v4
	v_add_u32_e32 v5, 0, v6
	v_lshrrev_b32_e32 v0, 5, v8
	v_mul_u32_u24_e32 v7, 0x84, v4
	v_lshlrev_b32_e32 v8, 2, v3
	v_and_b32_e32 v2, 31, v162
	v_add3_u32 v5, v5, v7, v8
	v_mul_u32_u24_e32 v7, 0x84, v0
	v_readlane_b32 s8, v253, 30
	v_or_b32_e32 v6, v6, v7
	v_lshlrev_b32_e32 v152, 2, v2
	v_readlane_b32 s9, v253, 31
	v_readlane_b32 s14, v253, 36
	v_readlane_b32 s15, v253, 37
	v_readlane_b32 s16, v253, 38
	v_readlane_b32 s17, v253, 39
	v_add_u32_e32 v46, 0xfe80, v9
	v_lshlrev_b32_e32 v8, 2, v0
	v_mov_b32_e32 v9, v153
	v_or_b32_e32 v40, 8, v3
	v_or_b32_e32 v41, 16, v3
	v_or_b32_e32 v42, 24, v3
	v_add3_u32 v43, v6, v152, 0
	v_lshl_add_u64 v[6:7], s[16:17], 0, v[152:153]
	v_lshlrev_b32_e32 v44, 5, v1
	v_or_b32_e32 v45, 14, v0
	v_lshl_add_u64 v[8:9], s[48:49], 0, v[8:9]
	v_or_b32_e32 v47, 12, v0
	v_or_b32_e32 v48, 10, v0
	v_or_b32_e32 v49, 8, v0
	v_or_b32_e32 v50, 6, v0
	v_or_b32_e32 v51, 4, v0
	v_or_b32_e32 v52, 2, v0
	v_lshl_add_u64 v[10:11], s[14:15], 0, v[152:153]
	s_waitcnt lgkmcnt(0)
	v_lshl_add_u64 v[12:13], s[8:9], 0, v[152:153]
	s_mov_b64 s[6:7], 0
	v_readlane_b32 s10, v253, 32
	v_readlane_b32 s11, v253, 33
	v_readlane_b32 s12, v253, 34
	v_readlane_b32 s13, v253, 35
	v_readlane_b32 s18, v253, 40
	v_readlane_b32 s19, v253, 41
	v_readlane_b32 s20, v253, 42
	v_readlane_b32 s21, v253, 43
	v_readlane_b32 s22, v253, 44
	v_readlane_b32 s23, v253, 45
	s_branch .LBB0_803
.LBB0_802:
	s_or_b64 exec, exec, s[8:9]
.Ltr_next:
	v_readlane_b32 s1, v253, 50
	v_readlane_b32 s0, v254, 54
	s_nop 0
	v_add_u32_e32 v1, s1, v1
	v_add_u32_e32 v44, s0, v44
	s_movk_i32 s0, 0x26ff
	v_cmp_lt_i32_e32 vcc, s0, v1
	s_or_b64 s[6:7], vcc, s[6:7]
	v_add_u32_e32 v46, s1, v46
	s_andn2_b64 exec, exec, s[6:7]
	s_cbranch_execz .LBB0_861
.LBB0_803:
.Ltr_item:
	v_readfirstlane_b32 s60, v1
	v_readlane_b32 s64, v253, 0
	v_readlane_b32 s65, v253, 1
	s_nop 3
	s_sub_u32 s64, s64, 0xd0
	s_subb_u32 s65, s65, 0
	s_load_dwordx2 s[66:67], s[64:65], 0xc0
	s_cmpk_ge_u32 s60, 0x1380
	s_cselect_b32 s10, 1, 0
	s_mulk_i32 s10, 0x1380
	s_sub_u32 s60, s60, s10
	s_cmp_lg_u32 s10, 0
	s_cselect_b32 s10, 1, 0
	s_cmpk_lt_u32 s60, 0x200
	s_cbranch_scc1 .Ltr_k_in
	s_cmpk_lt_u32 s60, 0x280
	s_cbranch_scc1 .Ltr_k_glu
	s_cmpk_lt_u32 s60, 0x380
	s_cbranch_scc1 .Ltr_k_out
	s_cmpk_lt_u32 s60, 0xb80
	s_cbranch_scc1 .Ltr_k_w1
	s_load_dwordx2 s[52:53], s[64:65], 0xa8
	s_mov_b64 s[56:57], 0
	s_sub_u32 s60, s60, 0xb80
	s_movk_i32 s62, 0x1000
	s_movk_i32 s63, 0x400
	s_mov_b32 s61, 5
	s_lshl_b32 s11, s10, 24
	s_mov_b32 s12, 0xd00000
	s_branch .Ltr_common
.Ltr_k_w1:
	s_load_dwordx2 s[52:53], s[64:65], 0xa0
	s_load_dwordx2 s[56:57], s[64:65], 0x30
	s_sub_u32 s60, s60, 0x380
	s_movk_i32 s62, 0x400
	s_movk_i32 s63, 0x1000
	s_mov_b32 s61, 7
	s_lshl_b32 s11, s10, 24
	s_mov_b32 s12, 0x500000
	s_branch .Ltr_common
.Ltr_k_out:
	s_load_dwordx2 s[52:53], s[64:65], 0x98
	s_mov_b64 s[56:57], 0
	s_sub_u32 s60, s60, 0x280
	s_movk_i32 s62, 0x400
	s_movk_i32 s63, 0x400
	s_mov_b32 s61, 5
	s_lshl_b32 s11, s10, 22
	s_mov_b32 s12, 0x300000
	s_branch .Ltr_common
.Ltr_k_glu:
	s_load_dwordx2 s[52:53], s[64:65], 0x80
	s_mov_b64 s[56:57], 0
	s_sub_u32 s60, s60, 0x200
	s_movk_i32 s62, 0x200
	s_movk_i32 s63, 0x200
	s_mov_b32 s61, 4
	s_lshl_b32 s11, s10, 20
	s_mov_b32 s12, 0x200000
	s_branch .Ltr_common
.Ltr_k_in:
	s_load_dwordx2 s[52:53], s[64:65], 0x38
	s_load_dwordx2 s[56:57], s[64:65], 0x28
	s_movk_i32 s62, 0x400
	s_movk_i32 s63, 0x400
	s_mov_b32 s61, 5
	s_lshl_b32 s11, s10, 22
	s_mov_b32 s12, 0x0
	s_branch .Ltr_common
.Ltr_common:
	s_waitcnt lgkmcnt(0)
	s_add_u32 s52, s52, s11
	s_addc_u32 s53, s53, 0
	s_lshl_b32 s13, s10, 12
	s_cmp_lg_u64 s[56:57], 0
	s_cselect_b32 s13, s13, 0
	s_add_u32 s56, s56, s13
	s_addc_u32 s57, s57, 0
	s_mul_i32 s13, s10, 0x2100000
	s_add_u32 s54, s66, s13
	s_addc_u32 s55, s67, 0
	s_add_u32 s54, s54, 0x400000
	s_addc_u32 s55, s55, 0
	s_add_u32 s54, s54, s12
	s_addc_u32 s55, s55, 0
	s_lshr_b32 s13, s60, s61
	s_lshl_b32 s14, s13, s61
	s_sub_u32 s14, s60, s14
	s_lshl_b32 s13, s13, 6
	s_lshl_b32 s14, s14, 5
	s_mul_i32 s15, s13, s63
	s_add_u32 s15, s15, s14
	s_lshl_b32 s15, s15, 2
	s_add_u32 s52, s52, s15
	s_addc_u32 s53, s53, 0
	s_cmp_lg_u64 s[56:57], 0
	s_cselect_b32 s16, 1, 0
	s_lshl_b32 s15, s13, 2
	s_add_u32 s56, s56, s15
	s_addc_u32 s57, s57, 0
	s_mul_i32 s15, s14, s62
	s_add_u32 s15, s15, s13
	s_lshl_b32 s15, s15, 1
	s_add_u32 s54, s54, s15
	s_addc_u32 s55, s55, 0
	s_lshl_b32 s58, s63, 3
	s_lshl_b32 s59, s62, 4
	v_and_b32_e32 v63, 63, v162
	v_lshrrev_b32_e32 v124, 5, v63
	v_mul_lo_u32 v124, v124, s63
	v_and_b32_e32 v125, 31, v63
	v_add_lshl_u32 v124, v124, v125, 2
	v_lshrrev_b32_e32 v126, 5, v63
	v_mul_u32_u24_e32 v126, 33, v126
	v_add_lshl_u32 v125, v126, v125, 2
	v_lshrrev_b32_e32 v127, 6, v162
	v_lshlrev_b32_e32 v127, 14, v127
	v_add_u32_e32 v125, v125, v127
	v_and_b32_e32 v126, 7, v63
	v_mul_u32_u24_e32 v126, 0x108, v126
	v_lshrrev_b32_e32 v120, 3, v63
	v_add_lshl_u32 v126, v126, v120, 2
	v_add_u32_e32 v126, v126, v127
	v_mul_lo_u32 v127, v120, s62
	v_and_b32_e32 v120, 7, v63
	v_lshl_add_u32 v127, v120, 3, v127
	v_lshlrev_b32_e32 v127, 1, v127
	v_lshlrev_b32_e32 v63, 5, v120
	s_cmp_eq_u32 s16, 0
	s_cbranch_scc1 .Ltr_nogk
	global_load_dwordx4 v[96:99], v63, s[56:57]
	global_load_dwordx4 v[100:103], v63, s[56:57] offset:16
; #define LAS __attribute__((address_space(3)))
; __device__ __forceinline__ unsigned pk2(float lo, float hi) { return pg8::cvt_pk_bf16(lo, hi); }
; __device__ __forceinline__ void transpose_item(const float* W, const float* gk, int K, int N, bf16_t* WT, LAS float* scr, int item, int lane) {
;     ...
;     for (int i = 0; i < 32; ++i) { const int kk = 2 * i + (lane >> 5); float v = __builtin_nontemporal_load(W + (size_t)(k0 + kk) * N + n0 + (lane & 31));   if (gk) v *= gk[k0 + kk]; scr[kk * 33 + (lane & 31)] = v; }
;     asm volatile("s_waitcnt lgkmcnt(0)" ::: "memory");
;     const int c = lane & 7;
; #pragma unroll
;     for (int j = 0; j < 4; ++j) { const int n = (lane >> 3) + 8 * j; const LAS float* s = scr + (8 * c) * 33 + n;
;         u32x4 o; o.x = pk2(s[0 * 33], s[1 * 33]); o.y = pk2(s[2 * 33], s[3 * 33]); o.z = pk2(s[4 * 33], s[5 * 33]); o.w = pk2(s[6 * 33], s[7 * 33]);
.Ltr_nogk:
	global_load_dword v64, v124, s[52:53] nt
	s_add_u32 s52, s52, s58
	s_addc_u32 s53, s53, 0
	global_load_dword v65, v124, s[52:53] nt
	s_add_u32 s52, s52, s58
	s_addc_u32 s53, s53, 0
	global_load_dword v66, v124, s[52:53] nt
	s_add_u32 s52, s52, s58
	s_addc_u32 s53, s53, 0
	global_load_dword v67, v124, s[52:53] nt
	s_add_u32 s52, s52, s58
	s_addc_u32 s53, s53, 0
	global_load_dword v68, v124, s[52:53] nt
	s_add_u32 s52, s52, s58
	s_addc_u32 s53, s53, 0
	global_load_dword v69, v124, s[52:53] nt
	s_add_u32 s52, s52, s58
	s_addc_u32 s53, s53, 0
	global_load_dword v70, v124, s[52:53] nt
	s_add_u32 s52, s52, s58
	s_addc_u32 s53, s53, 0
	global_load_dword v71, v124, s[52:53] nt
	s_add_u32 s52, s52, s58
	s_addc_u32 s53, s53, 0
	global_load_dword v72, v124, s[52:53] nt
	s_add_u32 s52, s52, s58
	s_addc_u32 s53, s53, 0
	global_load_dword v73, v124, s[52:53] nt
	s_add_u32 s52, s52, s58
	s_addc_u32 s53, s53, 0
	global_load_dword v74, v124, s[52:53] nt
	s_add_u32 s52, s52, s58
	s_addc_u32 s53, s53, 0
	global_load_dword v75, v124, s[52:53] nt
	s_add_u32 s52, s52, s58
	s_addc_u32 s53, s53, 0
	global_load_dword v76, v124, s[52:53] nt
	s_add_u32 s52, s52, s58
	s_addc_u32 s53, s53, 0
	global_load_dword v77, v124, s[52:53] nt
	s_add_u32 s52, s52, s58
	s_addc_u32 s53, s53, 0
	global_load_dword v78, v124, s[52:53] nt
	s_add_u32 s52, s52, s58
	s_addc_u32 s53, s53, 0
	global_load_dword v79, v124, s[52:53] nt
	s_add_u32 s52, s52, s58
	s_addc_u32 s53, s53, 0
	global_load_dword v80, v124, s[52:53] nt
	s_add_u32 s52, s52, s58
	s_addc_u32 s53, s53, 0
	global_load_dword v81, v124, s[52:53] nt
	s_add_u32 s52, s52, s58
	s_addc_u32 s53, s53, 0
	global_load_dword v82, v124, s[52:53] nt
	s_add_u32 s52, s52, s58
	s_addc_u32 s53, s53, 0
	global_load_dword v83, v124, s[52:53] nt
	s_add_u32 s52, s52, s58
	s_addc_u32 s53, s53, 0
	global_load_dword v84, v124, s[52:53] nt
	s_add_u32 s52, s52, s58
	s_addc_u32 s53, s53, 0
	global_load_dword v85, v124, s[52:53] nt
	s_add_u32 s52, s52, s58
	s_addc_u32 s53, s53, 0
	global_load_dword v86, v124, s[52:53] nt
	s_add_u32 s52, s52, s58
	s_addc_u32 s53, s53, 0
	global_load_dword v87, v124, s[52:53] nt
	s_add_u32 s52, s52, s58
	s_addc_u32 s53, s53, 0
	global_load_dword v88, v124, s[52:53] nt
	s_add_u32 s52, s52, s58
	s_addc_u32 s53, s53, 0
	global_load_dword v89, v124, s[52:53] nt
	s_add_u32 s52, s52, s58
	s_addc_u32 s53, s53, 0
	global_load_dword v90, v124, s[52:53] nt
	s_add_u32 s52, s52, s58
	s_addc_u32 s53, s53, 0
	global_load_dword v91, v124, s[52:53] nt
	s_add_u32 s52, s52, s58
	s_addc_u32 s53, s53, 0
	global_load_dword v92, v124, s[52:53] nt
	s_add_u32 s52, s52, s58
	s_addc_u32 s53, s53, 0
	global_load_dword v93, v124, s[52:53] nt
	s_add_u32 s52, s52, s58
	s_addc_u32 s53, s53, 0
	global_load_dword v94, v124, s[52:53] nt
	s_add_u32 s52, s52, s58
	s_addc_u32 s53, s53, 0
	global_load_dword v95, v124, s[52:53] nt
	s_waitcnt vmcnt(0)
	ds_write_b32 v125, v64 offset:0
	ds_write_b32 v125, v65 offset:264
	ds_write_b32 v125, v66 offset:528
	ds_write_b32 v125, v67 offset:792
	ds_write_b32 v125, v68 offset:1056
	ds_write_b32 v125, v69 offset:1320
	ds_write_b32 v125, v70 offset:1584
	ds_write_b32 v125, v71 offset:1848
	ds_write_b32 v125, v72 offset:2112
	ds_write_b32 v125, v73 offset:2376
	ds_write_b32 v125, v74 offset:2640
	ds_write_b32 v125, v75 offset:2904
	ds_write_b32 v125, v76 offset:3168
	ds_write_b32 v125, v77 offset:3432
	ds_write_b32 v125, v78 offset:3696
	ds_write_b32 v125, v79 offset:3960
	ds_write_b32 v125, v80 offset:4224
	ds_write_b32 v125, v81 offset:4488
	ds_write_b32 v125, v82 offset:4752
	ds_write_b32 v125, v83 offset:5016
	ds_write_b32 v125, v84 offset:5280
	ds_write_b32 v125, v85 offset:5544
	ds_write_b32 v125, v86 offset:5808
	ds_write_b32 v125, v87 offset:6072
	ds_write_b32 v125, v88 offset:6336
	ds_write_b32 v125, v89 offset:6600
	ds_write_b32 v125, v90 offset:6864
	ds_write_b32 v125, v91 offset:7128
	ds_write_b32 v125, v92 offset:7392
	ds_write_b32 v125, v93 offset:7656
	ds_write_b32 v125, v94 offset:7920
	ds_write_b32 v125, v95 offset:8184
	s_waitcnt lgkmcnt(0)
	ds_read2_b32 v[104:105], v126 offset0:0 offset1:33
	ds_read2_b32 v[106:107], v126 offset0:66 offset1:99
	ds_read2_b32 v[108:109], v126 offset0:132 offset1:165
	ds_read2_b32 v[110:111], v126 offset0:198 offset1:231
	s_waitcnt lgkmcnt(0)
	s_cmp_eq_u32 s16, 0
	s_cbranch_scc1 .Ltr_nm0
	v_mul_f32_e32 v104, v104, v96
	v_mul_f32_e32 v105, v105, v97
	v_mul_f32_e32 v106, v106, v98
	v_mul_f32_e32 v107, v107, v99
	v_mul_f32_e32 v108, v108, v100
	v_mul_f32_e32 v109, v109, v101
	v_mul_f32_e32 v110, v110, v102
	v_mul_f32_e32 v111, v111, v103
; #define LAS __attribute__((address_space(3)))
; __device__ __forceinline__ unsigned pk2(float lo, float hi) { return pg8::cvt_pk_bf16(lo, hi); }
; __device__ __forceinline__ void transpose_item(const float* W, const float* gk, int K, int N, bf16_t* WT, LAS float* scr, int item, int lane) {
;     ...
;     for (int j = 0; j < 4; ++j) { const int n = (lane >> 3) + 8 * j; const LAS float* s = scr + (8 * c) * 33 + n;
;         u32x4 o; o.x = pk2(s[0 * 33], s[1 * 33]); o.y = pk2(s[2 * 33], s[3 * 33]); o.z = pk2(s[4 * 33], s[5 * 33]); o.w = pk2(s[6 * 33], s[7 * 33]);
;         *(u32x4*)(WT + (size_t)(n0 + n) * K + k0 + 8 * c) = o; }
;     asm volatile("s_waitcnt lgkmcnt(0)" ::: "memory");
.Ltr_nm0:
	v_cvt_pk_bf16_f32 v120, v104, v105
	v_cvt_pk_bf16_f32 v121, v106, v107
	v_cvt_pk_bf16_f32 v122, v108, v109
	v_cvt_pk_bf16_f32 v123, v110, v111
	global_store_dwordx4 v127, v[120:123], s[54:55]
	s_add_u32 s54, s54, s59
	s_addc_u32 s55, s55, 0
	ds_read2_b32 v[104:105], v126 offset0:8 offset1:41
	ds_read2_b32 v[106:107], v126 offset0:74 offset1:107
	ds_read2_b32 v[108:109], v126 offset0:140 offset1:173
	ds_read2_b32 v[110:111], v126 offset0:206 offset1:239
	s_waitcnt lgkmcnt(0)
	s_cmp_eq_u32 s16, 0
	s_cbranch_scc1 .Ltr_nm1
	v_mul_f32_e32 v104, v104, v96
	v_mul_f32_e32 v105, v105, v97
	v_mul_f32_e32 v106, v106, v98
	v_mul_f32_e32 v107, v107, v99
	v_mul_f32_e32 v108, v108, v100
	v_mul_f32_e32 v109, v109, v101
	v_mul_f32_e32 v110, v110, v102
	v_mul_f32_e32 v111, v111, v103
.Ltr_nm1:
	v_cvt_pk_bf16_f32 v120, v104, v105
	v_cvt_pk_bf16_f32 v121, v106, v107
	v_cvt_pk_bf16_f32 v122, v108, v109
	v_cvt_pk_bf16_f32 v123, v110, v111
	global_store_dwordx4 v127, v[120:123], s[54:55]
	s_add_u32 s54, s54, s59
	s_addc_u32 s55, s55, 0
	ds_read2_b32 v[104:105], v126 offset0:16 offset1:49
	ds_read2_b32 v[106:107], v126 offset0:82 offset1:115
	ds_read2_b32 v[108:109], v126 offset0:148 offset1:181
	ds_read2_b32 v[110:111], v126 offset0:214 offset1:247
	s_waitcnt lgkmcnt(0)
	s_cmp_eq_u32 s16, 0
	s_cbranch_scc1 .Ltr_nm2
	v_mul_f32_e32 v104, v104, v96
	v_mul_f32_e32 v105, v105, v97
	v_mul_f32_e32 v106, v106, v98
	v_mul_f32_e32 v107, v107, v99
	v_mul_f32_e32 v108, v108, v100
	v_mul_f32_e32 v109, v109, v101
	v_mul_f32_e32 v110, v110, v102
	v_mul_f32_e32 v111, v111, v103
.Ltr_nm2:
	v_cvt_pk_bf16_f32 v120, v104, v105
	v_cvt_pk_bf16_f32 v121, v106, v107
	v_cvt_pk_bf16_f32 v122, v108, v109
	v_cvt_pk_bf16_f32 v123, v110, v111
	global_store_dwordx4 v127, v[120:123], s[54:55]
	s_add_u32 s54, s54, s59
	s_addc_u32 s55, s55, 0
	ds_read2_b32 v[104:105], v126 offset0:24 offset1:57
	ds_read2_b32 v[106:107], v126 offset0:90 offset1:123
	ds_read2_b32 v[108:109], v126 offset0:156 offset1:189
	ds_read2_b32 v[110:111], v126 offset0:222 offset1:255
	s_waitcnt lgkmcnt(0)
	s_cmp_eq_u32 s16, 0
	s_cbranch_scc1 .Ltr_nm3
	v_mul_f32_e32 v104, v104, v96
	v_mul_f32_e32 v105, v105, v97
	v_mul_f32_e32 v106, v106, v98
	v_mul_f32_e32 v107, v107, v99
	v_mul_f32_e32 v108, v108, v100
	v_mul_f32_e32 v109, v109, v101
	v_mul_f32_e32 v110, v110, v102
	v_mul_f32_e32 v111, v111, v103
.Ltr_nm3:
	v_cvt_pk_bf16_f32 v120, v104, v105
	v_cvt_pk_bf16_f32 v121, v106, v107
	v_cvt_pk_bf16_f32 v122, v108, v109
	v_cvt_pk_bf16_f32 v123, v110, v111
	global_store_dwordx4 v127, v[120:123], s[54:55]
	s_branch .Ltr_next
